# gate loads with sc0 nt (was nt)
# baseline (speedup 1.0000x reference)
; __device__ __forceinline__ float bf_lo(unsigned w) { return __uint_as_float(w << 16); }
; __device__ __forceinline__ float bf_hi(unsigned w) { return __uint_as_float(w & 0xffff0000u); }
;     __device__ __forceinline__ bool operator()(f32x4 (&acc)[2][2][4][2], const Unit& u, int wr, int wc, int fr, int fq) const {
;         const int r0 = u.pm * BM + wr * 64 + fr, c0 = u.pn * BM + wc * 32 + fq * 8;
;         const bf16_t* S = u.kh ? SGB : SGR;
; #pragma unroll
;         for (int ai = 0; ai < 2; ++ai)
; #pragma unroll
;             for (int m = 0; m < 4; ++m) { const size_t off = (size_t)(r0 + ai * HALF + m * 16) * D + c0;
; #pragma unroll
;                 for (int bj = 0; bj < 2; ++bj) { const u32x4 s = *(const u32x4*)(S + off + bj * HALF);
;                     f32x4 v0 = acc[ai][bj][m][0], v1 = acc[ai][bj][m][1];
;                     v0[0] *= bf_lo(s.x); v0[1] *= bf_hi(s.x); v0[2] *= bf_lo(s.y); v0[3] *= bf_hi(s.y);
;                     v1[0] *= bf_lo(s.z); v1[1] *= bf_hi(s.z); v1[2] *= bf_lo(s.w); v1[3] *= bf_hi(s.w);
;                     acc[ai][bj][m][0] = v0; acc[ai][bj][m][1] = v1; } }
;     __device__ __forceinline__ bool operator()(f32x4 (&acc)[2][2][4][2], const Unit& u, int wr, int wc, int fr, int fq) const {
;         if (u.type == 0) return d(acc, u, wr, wc, fr, fq);
.Lkepi_sa:
	s_cmp_lg_u32 s65, 0
	s_cselect_b64 s[42:43], -1, 0
	s_cmp_eq_u32 s65, 0
	s_cselect_b64 s[0:1], -1, 0
	s_and_b64 vcc, s[0:1], exec
	v_lshl_add_u32 v160, s64, 8, v1
	v_lshl_or_b32 v158, s66, 8, v173
	s_cselect_b32 s0, s5, s15
	s_cselect_b32 s1, s4, s14
	v_mov_b32_e32 v130, s1
	v_mov_b32_e32 v131, s0
	v_ashrrev_i32_e32 v159, 31, v158
	v_ashrrev_i32_e32 v161, 31, v160
	v_lshl_add_u64 v[170:171], v[158:159], 1, v[130:131]
	v_lshlrev_b64 v[130:131], 12, v[160:161]
	v_or_b32_e32 v162, 16, v160
	v_lshl_add_u64 v[130:131], v[170:171], 0, v[130:131]
	v_ashrrev_i32_e32 v163, 31, v162
	v_mov_b64_e32 v[228:229], v[130:131]
	global_load_dwordx4 v[142:145], v[130:131], off sc0 nt
	global_load_dwordx4 v[176:179], v[130:131], off offset:256 sc0 nt
	v_lshlrev_b64 v[130:131], 12, v[162:163]
	v_or_b32_e32 v164, 32, v160
	v_lshl_add_u64 v[130:131], v[170:171], 0, v[130:131]
	v_ashrrev_i32_e32 v165, 31, v164
	global_load_dwordx4 v[180:183], v[130:131], off sc0 nt
	global_load_dwordx4 v[184:187], v[130:131], off offset:256 sc0 nt
	v_lshlrev_b64 v[130:131], 12, v[164:165]
	v_lshl_add_u64 v[130:131], v[170:171], 0, v[130:131]
	global_load_dwordx4 v[192:195], v[130:131], off sc0 nt
	global_load_dwordx4 v[196:199], v[130:131], off offset:256 sc0 nt
	v_or_b32_e32 v166, 48, v160
	v_add_u32_e32 v168, 0x80, v160
	v_ashrrev_i32_e32 v167, 31, v166
	v_ashrrev_i32_e32 v169, 31, v168
	v_lshlrev_b64 v[130:131], 12, v[166:167]
	v_lshlrev_b64 v[132:133], 12, v[168:169]
	v_lshl_add_u64 v[130:131], v[170:171], 0, v[130:131]
	v_lshl_add_u64 v[134:135], v[170:171], 0, v[132:133]
	global_load_dwordx4 v[200:203], v[130:131], off sc0 nt
	global_load_dwordx4 v[138:141], v[130:131], off offset:256 sc0 nt
	s_nop 0
	global_load_dwordx4 v[130:133], v[134:135], off sc0 nt
	s_nop 0
	global_load_dwordx4 v[134:137], v[134:135], off offset:256 sc0 nt
	s_mov_b64 s[0:1], 0x90000
	v_lshl_add_u64 v[226:227], v[228:229], 0, s[0:1]
	global_load_dwordx4 v[232:235], v[226:227], off sc0 nt
	global_load_dwordx4 v[236:239], v[226:227], off offset:256 sc0 nt
	s_mov_b64 s[0:1], 0xa0000
	v_lshl_add_u64 v[226:227], v[228:229], 0, s[0:1]
	global_load_dwordx4 v[240:243], v[226:227], off sc0 nt
	global_load_dwordx4 v[244:247], v[226:227], off offset:256 sc0 nt
	s_mov_b64 s[0:1], 0xb0000
	v_lshl_add_u64 v[226:227], v[228:229], 0, s[0:1]
	global_load_dwordx4 v[248:251], v[226:227], off sc0 nt
	global_load_dwordx4 v[252:255], v[226:227], off offset:256 sc0 nt
	s_waitcnt vmcnt(0)
	v_lshlrev_b32_e32 v188, 16, v142
	v_and_b32_e32 v189, 0xffff0000, v142
	v_lshlrev_b32_e32 v142, 16, v143
	v_and_b32_e32 v143, 0xffff0000, v143
	v_pk_mul_f32 v[128:129], v[128:129], v[142:143]
	v_lshlrev_b32_e32 v204, 16, v144
	v_and_b32_e32 v205, 0xffff0000, v144
	v_lshlrev_b32_e32 v144, 16, v145
	v_lshlrev_b32_e32 v142, 16, v192
	v_and_b32_e32 v143, 0xffff0000, v192
	v_pk_mul_f32 v[110:111], v[110:111], v[142:143]
	v_lshlrev_b32_e32 v142, 16, v193
	v_and_b32_e32 v143, 0xffff0000, v193
	v_pk_mul_f32 v[112:113], v[112:113], v[142:143]
	v_add_u32_e32 v142, 0x90, v160
	v_and_b32_e32 v145, 0xffff0000, v145
	v_ashrrev_i32_e32 v143, 31, v142
	v_lshlrev_b32_e32 v210, 16, v180
	v_and_b32_e32 v211, 0xffff0000, v180
	v_lshlrev_b32_e32 v180, 16, v181
	v_and_b32_e32 v181, 0xffff0000, v181
	v_pk_mul_f32 v[124:125], v[124:125], v[144:145]
	v_lshlrev_b64 v[144:145], 12, v[142:143]
	v_lshlrev_b32_e32 v206, 16, v176
	v_and_b32_e32 v207, 0xffff0000, v176
	v_lshlrev_b32_e32 v176, 16, v177
	v_and_b32_e32 v177, 0xffff0000, v177
	v_lshlrev_b32_e32 v208, 16, v178
	v_and_b32_e32 v209, 0xffff0000, v178
	v_lshlrev_b32_e32 v178, 16, v179
	v_and_b32_e32 v179, 0xffff0000, v179
	v_pk_mul_f32 v[120:121], v[120:121], v[180:181]
	v_lshl_add_u64 v[144:145], v[170:171], 0, v[144:145]
	v_lshlrev_b32_e32 v180, 16, v194
	v_and_b32_e32 v181, 0xffff0000, v194
	v_pk_mul_f32 v[96:97], v[96:97], v[176:177]
	v_pk_mul_f32 v[92:93], v[92:93], v[178:179]
	v_mov_b64_e32 v[176:177], v[232:233]
	v_mov_b64_e32 v[178:179], v[234:235]
	v_pk_mul_f32 v[106:107], v[106:107], v[180:181]
	v_lshlrev_b32_e32 v180, 16, v195
	v_and_b32_e32 v181, 0xffff0000, v195
	v_lshlrev_b32_e32 v212, 16, v182
	v_and_b32_e32 v213, 0xffff0000, v182
	v_lshlrev_b32_e32 v182, 16, v183
	v_and_b32_e32 v183, 0xffff0000, v183
	v_pk_mul_f32 v[108:109], v[108:109], v[180:181]
	v_lshlrev_b32_e32 v180, 16, v196
	v_and_b32_e32 v181, 0xffff0000, v196
	v_pk_mul_f32 v[116:117], v[116:117], v[182:183]
	v_pk_mul_f32 v[78:79], v[78:79], v[180:181]
	v_mov_b64_e32 v[180:181], v[236:237]
	v_mov_b64_e32 v[182:183], v[238:239]
	v_lshlrev_b32_e32 v144, 16, v198
	v_and_b32_e32 v145, 0xffff0000, v198
	v_pk_mul_f32 v[74:75], v[74:75], v[144:145]
	v_lshlrev_b32_e32 v144, 16, v199
	v_and_b32_e32 v145, 0xffff0000, v199
	v_lshlrev_b32_e32 v214, 16, v184
	v_and_b32_e32 v215, 0xffff0000, v184
	v_lshlrev_b32_e32 v184, 16, v185
	v_and_b32_e32 v185, 0xffff0000, v185
	v_pk_mul_f32 v[76:77], v[76:77], v[144:145]
	v_add_u32_e32 v144, 0xa0, v160
	v_pk_mul_f32 v[88:89], v[88:89], v[184:185]
	v_lshlrev_b32_e32 v184, 16, v197
	v_and_b32_e32 v185, 0xffff0000, v197
	v_ashrrev_i32_e32 v145, 31, v144
	v_pk_mul_f32 v[80:81], v[80:81], v[184:185]
	v_lshlrev_b64 v[184:185], 12, v[144:145]
	v_lshlrev_b32_e32 v216, 16, v186
	v_and_b32_e32 v217, 0xffff0000, v186
	v_lshlrev_b32_e32 v186, 16, v187
	v_and_b32_e32 v187, 0xffff0000, v187
	v_pk_mul_f32 v[126:127], v[126:127], v[188:189]
	v_lshl_add_u64 v[188:189], v[170:171], 0, v[184:185]
	v_pk_mul_f32 v[84:85], v[84:85], v[186:187]
	v_mov_b64_e32 v[184:185], v[240:241]
	v_mov_b64_e32 v[186:187], v[242:243]
	v_lshlrev_b32_e32 v192, 16, v200
	v_and_b32_e32 v193, 0xffff0000, v200
	v_pk_mul_f32 v[102:103], v[102:103], v[192:193]
; __device__ __forceinline__ float bf_lo(unsigned w) { return __uint_as_float(w << 16); }
; __device__ __forceinline__ float bf_hi(unsigned w) { return __uint_as_float(w & 0xffff0000u); }
;     __device__ __forceinline__ bool operator()(f32x4 (&acc)[2][2][4][2], const Unit& u, int wr, int wc, int fr, int fq) const {
;     ...
;                 for (int bj = 0; bj < 2; ++bj) { const u32x4 s = *(const u32x4*)(S + off + bj * HALF);
;                     f32x4 v0 = acc[ai][bj][m][0], v1 = acc[ai][bj][m][1];
;                     v0[0] *= bf_lo(s.x); v0[1] *= bf_hi(s.x); v0[2] *= bf_lo(s.y); v0[3] *= bf_hi(s.y);
;                     v1[0] *= bf_lo(s.z); v1[1] *= bf_hi(s.z); v1[2] *= bf_lo(s.w); v1[3] *= bf_hi(s.w);
;                     acc[ai][bj][m][0] = v0; acc[ai][bj][m][1] = v1; } }
;         if (u.kh == 0) return false;
	v_lshlrev_b32_e32 v192, 16, v201
	v_and_b32_e32 v193, 0xffff0000, v201
	v_pk_mul_f32 v[104:105], v[104:105], v[192:193]
	v_lshlrev_b32_e32 v192, 16, v202
	v_and_b32_e32 v193, 0xffff0000, v202
	v_pk_mul_f32 v[98:99], v[98:99], v[192:193]
	v_mov_b64_e32 v[192:193], v[244:245]
	v_mov_b64_e32 v[194:195], v[246:247]
	v_lshlrev_b32_e32 v188, 16, v138
	v_and_b32_e32 v189, 0xffff0000, v138
	v_lshlrev_b32_e32 v138, 16, v139
	v_and_b32_e32 v139, 0xffff0000, v139
	v_pk_mul_f32 v[72:73], v[72:73], v[138:139]
	v_add_u32_e32 v138, 0xb0, v160
	v_ashrrev_i32_e32 v139, 31, v138
	v_pk_mul_f32 v[70:71], v[70:71], v[188:189]
	v_lshlrev_b64 v[188:189], 12, v[138:139]
	v_lshlrev_b32_e32 v196, 16, v203
	v_and_b32_e32 v197, 0xffff0000, v203
	v_lshl_add_u64 v[170:171], v[170:171], 0, v[188:189]
	v_pk_mul_f32 v[100:101], v[100:101], v[196:197]
	v_mov_b64_e32 v[196:197], v[248:249]
	v_mov_b64_e32 v[198:199], v[250:251]
	v_mov_b64_e32 v[200:201], v[252:253]
	v_mov_b64_e32 v[202:203], v[254:255]
	v_lshlrev_b32_e32 v188, 16, v140
	v_and_b32_e32 v189, 0xffff0000, v140
	v_lshlrev_b32_e32 v140, 16, v141
	v_and_b32_e32 v141, 0xffff0000, v141
	v_pk_mul_f32 v[68:69], v[68:69], v[140:141]
	v_lshlrev_b32_e32 v140, 16, v130
	v_and_b32_e32 v141, 0xffff0000, v130
	v_lshlrev_b32_e32 v130, 16, v131
	v_and_b32_e32 v131, 0xffff0000, v131
	v_pk_mul_f32 v[64:65], v[64:65], v[130:131]
	v_lshlrev_b32_e32 v130, 16, v132
	v_and_b32_e32 v131, 0xffff0000, v132
	v_pk_mul_f32 v[58:59], v[58:59], v[130:131]
	v_lshlrev_b32_e32 v130, 16, v133
	v_and_b32_e32 v131, 0xffff0000, v133
	v_pk_mul_f32 v[60:61], v[60:61], v[130:131]
	v_lshlrev_b32_e32 v130, 16, v134
	v_and_b32_e32 v131, 0xffff0000, v134
	v_pk_mul_f32 v[30:31], v[30:31], v[130:131]
	v_lshlrev_b32_e32 v130, 16, v135
	v_and_b32_e32 v131, 0xffff0000, v135
	v_pk_mul_f32 v[32:33], v[32:33], v[130:131]
	v_lshlrev_b32_e32 v130, 16, v136
	v_and_b32_e32 v131, 0xffff0000, v136
	v_pk_mul_f32 v[26:27], v[26:27], v[130:131]
	v_lshlrev_b32_e32 v130, 16, v137
	v_and_b32_e32 v131, 0xffff0000, v137
	v_pk_mul_f32 v[28:29], v[28:29], v[130:131]
	s_waitcnt vmcnt(0)
	v_lshlrev_b32_e32 v130, 16, v176
	v_and_b32_e32 v131, 0xffff0000, v176
	v_pk_mul_f32 v[54:55], v[54:55], v[130:131]
	v_lshlrev_b32_e32 v130, 16, v177
	v_and_b32_e32 v131, 0xffff0000, v177
	v_pk_mul_f32 v[56:57], v[56:57], v[130:131]
	v_lshlrev_b32_e32 v130, 16, v178
	v_and_b32_e32 v131, 0xffff0000, v178
	v_pk_mul_f32 v[50:51], v[50:51], v[130:131]
	v_lshlrev_b32_e32 v130, 16, v179
	v_and_b32_e32 v131, 0xffff0000, v179
	v_pk_mul_f32 v[52:53], v[52:53], v[130:131]
	v_lshlrev_b32_e32 v130, 16, v180
	v_and_b32_e32 v131, 0xffff0000, v180
	v_pk_mul_f32 v[22:23], v[22:23], v[130:131]
	v_lshlrev_b32_e32 v130, 16, v181
	v_and_b32_e32 v131, 0xffff0000, v181
	v_pk_mul_f32 v[24:25], v[24:25], v[130:131]
	v_lshlrev_b32_e32 v130, 16, v182
	v_and_b32_e32 v131, 0xffff0000, v182
	v_pk_mul_f32 v[18:19], v[18:19], v[130:131]
	v_lshlrev_b32_e32 v130, 16, v183
	v_and_b32_e32 v131, 0xffff0000, v183
	v_pk_mul_f32 v[20:21], v[20:21], v[130:131]
	v_pk_mul_f32 v[122:123], v[122:123], v[204:205]
	v_pk_mul_f32 v[94:95], v[94:95], v[206:207]
	v_lshlrev_b32_e32 v130, 16, v184
	v_and_b32_e32 v131, 0xffff0000, v184
	v_pk_mul_f32 v[46:47], v[46:47], v[130:131]
	v_lshlrev_b32_e32 v130, 16, v185
	v_and_b32_e32 v131, 0xffff0000, v185
	v_pk_mul_f32 v[48:49], v[48:49], v[130:131]
	v_lshlrev_b32_e32 v130, 16, v186
	v_and_b32_e32 v131, 0xffff0000, v186
	v_pk_mul_f32 v[42:43], v[42:43], v[130:131]
	v_lshlrev_b32_e32 v130, 16, v187
	v_and_b32_e32 v131, 0xffff0000, v187
	v_pk_mul_f32 v[44:45], v[44:45], v[130:131]
	v_lshlrev_b32_e32 v130, 16, v192
	v_and_b32_e32 v131, 0xffff0000, v192
	v_pk_mul_f32 v[14:15], v[14:15], v[130:131]
	v_lshlrev_b32_e32 v130, 16, v193
	v_and_b32_e32 v131, 0xffff0000, v193
	v_pk_mul_f32 v[16:17], v[16:17], v[130:131]
	v_lshlrev_b32_e32 v130, 16, v194
	v_and_b32_e32 v131, 0xffff0000, v194
	v_pk_mul_f32 v[10:11], v[10:11], v[130:131]
	v_lshlrev_b32_e32 v130, 16, v195
	v_and_b32_e32 v131, 0xffff0000, v195
	v_pk_mul_f32 v[12:13], v[12:13], v[130:131]
	v_lshlrev_b32_e32 v130, 16, v196
	v_and_b32_e32 v131, 0xffff0000, v196
	v_pk_mul_f32 v[38:39], v[38:39], v[130:131]
	v_lshlrev_b32_e32 v130, 16, v197
	v_and_b32_e32 v131, 0xffff0000, v197
	v_pk_mul_f32 v[40:41], v[40:41], v[130:131]
	v_lshlrev_b32_e32 v130, 16, v198
	v_and_b32_e32 v131, 0xffff0000, v198
	v_pk_mul_f32 v[34:35], v[34:35], v[130:131]
	v_lshlrev_b32_e32 v130, 16, v199
	v_and_b32_e32 v131, 0xffff0000, v199
	v_pk_mul_f32 v[36:37], v[36:37], v[130:131]
	v_lshlrev_b32_e32 v130, 16, v200
	v_and_b32_e32 v131, 0xffff0000, v200
	v_pk_mul_f32 v[6:7], v[6:7], v[130:131]
	v_lshlrev_b32_e32 v130, 16, v201
	v_and_b32_e32 v131, 0xffff0000, v201
	v_pk_mul_f32 v[8:9], v[8:9], v[130:131]
	v_lshlrev_b32_e32 v130, 16, v202
	v_and_b32_e32 v131, 0xffff0000, v202
	v_pk_mul_f32 v[2:3], v[2:3], v[130:131]
	v_lshlrev_b32_e32 v130, 16, v203
	v_and_b32_e32 v131, 0xffff0000, v203
	v_pk_mul_f32 v[90:91], v[90:91], v[208:209]
	v_pk_mul_f32 v[118:119], v[118:119], v[210:211]
	v_pk_mul_f32 v[114:115], v[114:115], v[212:213]
	v_pk_mul_f32 v[86:87], v[86:87], v[214:215]
	v_pk_mul_f32 v[82:83], v[82:83], v[216:217]
	v_pk_mul_f32 v[66:67], v[66:67], v[188:189]
	v_pk_mul_f32 v[62:63], v[62:63], v[140:141]
	v_pk_mul_f32 v[4:5], v[4:5], v[130:131]
	s_cbranch_vccnz .LBB0_818
; __device__ __forceinline__ unsigned pk_bf16(float lo, float hi) { const f32x2_t v = {lo, hi}; return __builtin_bit_cast(unsigned, __builtin_convertvector(v, bf16x2_t)); }
;     __device__ __forceinline__ bool operator()(f32x4 (&acc)[2][2][4][2], const Unit& u, int wr, int wc, int fr, int fq) const {
;     ...
; #pragma unroll
;         for (int ai = 0; ai < 2; ++ai)
; #pragma unroll
;             for (int m = 0; m < 4; ++m) { const size_t off = (size_t)(r0 + ai * HALF + m * 16) * LDP + c0;
; #pragma unroll
;                 for (int bj = 0; bj < 2; ++bj) { const f32x4 v0 = acc[ai][bj][m][0], v1 = acc[ai][bj][m][1];
;                     u32x4 w; w.x = pk_bf16(v0[0], v0[1]); w.y = pk_bf16(v0[2], v0[3]); w.z = pk_bf16(v1[0], v1[1]); w.w = pk_bf16(v1[2], v1[3]);
;                     *(u32x4*)(MG + off + bj * HALF) = w; } }
	v_mov_b64_e32 v[134:135], s[12:13]
	v_mad_i64_i32 v[136:137], s[0:1], v160, s60, v[134:135]
	v_lshlrev_b64 v[140:141], 1, v[158:159]
	v_cvt_pk_bf16_f32 v130, v126, v127
	v_cvt_pk_bf16_f32 v131, v128, v129
	v_cvt_pk_bf16_f32 v132, v122, v123
	v_cvt_pk_bf16_f32 v133, v124, v125
	v_lshl_add_u64 v[136:137], v[136:137], 0, v[140:141]
	global_store_dwordx4 v[136:137], v[130:133], off
	s_nop 1
	v_cvt_pk_bf16_f32 v130, v94, v95
	v_cvt_pk_bf16_f32 v131, v96, v97
	v_cvt_pk_bf16_f32 v132, v90, v91
	v_cvt_pk_bf16_f32 v133, v92, v93
	global_store_dwordx4 v[136:137], v[130:133], off offset:256
	v_mad_i64_i32 v[136:137], s[0:1], v162, s60, v[134:135]
	s_nop 0
	v_cvt_pk_bf16_f32 v130, v118, v119
	v_cvt_pk_bf16_f32 v131, v120, v121
	v_cvt_pk_bf16_f32 v132, v114, v115
	v_cvt_pk_bf16_f32 v133, v116, v117
	v_lshl_add_u64 v[136:137], v[136:137], 0, v[140:141]
	global_store_dwordx4 v[136:137], v[130:133], off
	s_nop 1
	v_cvt_pk_bf16_f32 v130, v86, v87
	v_cvt_pk_bf16_f32 v131, v88, v89
	v_cvt_pk_bf16_f32 v132, v82, v83
	v_cvt_pk_bf16_f32 v133, v84, v85
	global_store_dwordx4 v[136:137], v[130:133], off offset:256
	v_mad_i64_i32 v[136:137], s[0:1], v164, s60, v[134:135]
	s_nop 0
	v_cvt_pk_bf16_f32 v130, v110, v111
	v_cvt_pk_bf16_f32 v131, v112, v113
	v_cvt_pk_bf16_f32 v132, v106, v107
	v_cvt_pk_bf16_f32 v133, v108, v109
	v_lshl_add_u64 v[136:137], v[136:137], 0, v[140:141]
	global_store_dwordx4 v[136:137], v[130:133], off
	s_nop 1
	v_cvt_pk_bf16_f32 v130, v78, v79
	v_cvt_pk_bf16_f32 v131, v80, v81
	v_cvt_pk_bf16_f32 v132, v74, v75
	v_cvt_pk_bf16_f32 v133, v76, v77
	global_store_dwordx4 v[136:137], v[130:133], off offset:256
	v_mad_i64_i32 v[136:137], s[0:1], v166, s60, v[134:135]
	s_nop 0
	v_cvt_pk_bf16_f32 v130, v102, v103
	v_cvt_pk_bf16_f32 v131, v104, v105
	v_cvt_pk_bf16_f32 v132, v98, v99
	v_cvt_pk_bf16_f32 v133, v100, v101
	v_lshl_add_u64 v[136:137], v[136:137], 0, v[140:141]
	global_store_dwordx4 v[136:137], v[130:133], off
	s_nop 1
	v_cvt_pk_bf16_f32 v130, v70, v71
	v_cvt_pk_bf16_f32 v131, v72, v73
	v_cvt_pk_bf16_f32 v132, v66, v67
	v_cvt_pk_bf16_f32 v133, v68, v69
	global_store_dwordx4 v[136:137], v[130:133], off offset:256
	v_mad_i64_i32 v[136:137], s[0:1], v168, s60, v[134:135]
	s_nop 0
	v_cvt_pk_bf16_f32 v130, v62, v63
	v_cvt_pk_bf16_f32 v131, v64, v65
	v_cvt_pk_bf16_f32 v132, v58, v59
	v_cvt_pk_bf16_f32 v133, v60, v61
	v_lshl_add_u64 v[136:137], v[136:137], 0, v[140:141]
	global_store_dwordx4 v[136:137], v[130:133], off
	s_nop 1
	v_cvt_pk_bf16_f32 v130, v30, v31
	v_cvt_pk_bf16_f32 v131, v32, v33
	v_cvt_pk_bf16_f32 v132, v26, v27
	v_cvt_pk_bf16_f32 v133, v28, v29
	global_store_dwordx4 v[136:137], v[130:133], off offset:256
	v_mad_i64_i32 v[136:137], s[0:1], v142, s60, v[134:135]
	s_nop 0
	v_cvt_pk_bf16_f32 v130, v54, v55
	v_cvt_pk_bf16_f32 v131, v56, v57
	v_cvt_pk_bf16_f32 v132, v50, v51
	v_cvt_pk_bf16_f32 v133, v52, v53
	v_lshl_add_u64 v[136:137], v[136:137], 0, v[140:141]
	global_store_dwordx4 v[136:137], v[130:133], off
	s_nop 1
	v_cvt_pk_bf16_f32 v130, v22, v23
	v_cvt_pk_bf16_f32 v131, v24, v25
	v_cvt_pk_bf16_f32 v132, v18, v19
	v_cvt_pk_bf16_f32 v133, v20, v21
	global_store_dwordx4 v[136:137], v[130:133], off offset:256
	v_mad_i64_i32 v[136:137], s[0:1], v144, s60, v[134:135]
	s_nop 0
	v_cvt_pk_bf16_f32 v130, v46, v47
	v_cvt_pk_bf16_f32 v131, v48, v49
	v_cvt_pk_bf16_f32 v132, v42, v43
	v_cvt_pk_bf16_f32 v133, v44, v45
	v_lshl_add_u64 v[136:137], v[136:137], 0, v[140:141]
	global_store_dwordx4 v[136:137], v[130:133], off
	v_mad_i64_i32 v[134:135], s[0:1], v138, s60, v[134:135]
	s_nop 0
	v_cvt_pk_bf16_f32 v130, v14, v15
	v_cvt_pk_bf16_f32 v131, v16, v17
	v_cvt_pk_bf16_f32 v132, v10, v11
	v_cvt_pk_bf16_f32 v133, v12, v13
	global_store_dwordx4 v[136:137], v[130:133], off offset:256
	v_lshl_add_u64 v[134:135], v[134:135], 0, v[140:141]
	s_nop 0
	v_cvt_pk_bf16_f32 v130, v38, v39
	v_cvt_pk_bf16_f32 v131, v40, v41
	v_cvt_pk_bf16_f32 v132, v34, v35
	v_cvt_pk_bf16_f32 v133, v36, v37
	global_store_dwordx4 v[134:135], v[130:133], off
	s_nop 1
	v_cvt_pk_bf16_f32 v130, v6, v7
	v_cvt_pk_bf16_f32 v131, v8, v9
	v_cvt_pk_bf16_f32 v132, v2, v3
	v_cvt_pk_bf16_f32 v133, v4, v5
	global_store_dwordx4 v[134:135], v[130:133], off offset:256

; __device__ __forceinline__ float bf_lo(unsigned w) { return __uint_as_float(w << 16); }
; __device__ __forceinline__ float bf_hi(unsigned w) { return __uint_as_float(w & 0xffff0000u); }
;     __device__ __forceinline__ bool operator()(f32x4 (&acc)[2][2][4][2], const Unit& u, int wr, int wc, int fr, int fq) const {
;         const int r0 = u.pm * BM + wr * 64 + fr, c0 = u.pn * BM + wc * 32 + fq * 8;
;         const bf16_t* S = u.kh ? SGB : SGR;
; #pragma unroll
;         for (int ai = 0; ai < 2; ++ai)
; #pragma unroll
;             for (int m = 0; m < 4; ++m) { const size_t off = (size_t)(r0 + ai * HALF + m * 16) * D + c0;
; #pragma unroll
;                 for (int bj = 0; bj < 2; ++bj) { const u32x4 s = *(const u32x4*)(S + off + bj * HALF);
;                     f32x4 v0 = acc[ai][bj][m][0], v1 = acc[ai][bj][m][1];
;                     v0[0] *= bf_lo(s.x); v0[1] *= bf_hi(s.x); v0[2] *= bf_lo(s.y); v0[3] *= bf_hi(s.y);
;                     v1[0] *= bf_lo(s.z); v1[1] *= bf_hi(s.z); v1[2] *= bf_lo(s.w); v1[3] *= bf_hi(s.w);
;                     acc[ai][bj][m][0] = v0; acc[ai][bj][m][1] = v1; } }
.LBB0_902:
	s_cmp_eq_u32 s66, 0
	v_lshl_add_u32 v160, s65, 8, v1
	v_lshl_or_b32 v158, s64, 8, v175
	s_cselect_b32 s0, s4, s14
	s_cselect_b32 s1, s5, s15
	v_mov_b32_e32 v130, s0
	v_mov_b32_e32 v131, s1
	v_ashrrev_i32_e32 v159, 31, v158
	v_ashrrev_i32_e32 v161, 31, v160
	v_lshl_add_u64 v[170:171], v[158:159], 1, v[130:131]
	v_lshlrev_b64 v[130:131], 12, v[160:161]
	v_or_b32_e32 v162, 16, v160
	v_lshl_add_u64 v[130:131], v[170:171], 0, v[130:131]
	v_ashrrev_i32_e32 v163, 31, v162
	global_load_dwordx4 v[142:145], v[130:131], off sc0 nt
	global_load_dwordx4 v[178:181], v[130:131], off offset:256 sc0 nt
	v_lshlrev_b64 v[130:131], 12, v[162:163]
	v_or_b32_e32 v164, 32, v160
	v_lshl_add_u64 v[130:131], v[170:171], 0, v[130:131]
	v_ashrrev_i32_e32 v165, 31, v164
	global_load_dwordx4 v[182:185], v[130:131], off sc0 nt
	global_load_dwordx4 v[186:189], v[130:131], off offset:256 sc0 nt
	v_lshlrev_b64 v[130:131], 12, v[164:165]
	v_lshl_add_u64 v[130:131], v[170:171], 0, v[130:131]
	global_load_dwordx4 v[192:195], v[130:131], off sc0 nt
	global_load_dwordx4 v[196:199], v[130:131], off offset:256 sc0 nt
	v_or_b32_e32 v166, 48, v160
	v_add_u32_e32 v168, 0x80, v160
	v_ashrrev_i32_e32 v167, 31, v166
	v_ashrrev_i32_e32 v169, 31, v168
	v_lshlrev_b64 v[130:131], 12, v[166:167]
	v_lshlrev_b64 v[132:133], 12, v[168:169]
	v_lshl_add_u64 v[130:131], v[170:171], 0, v[130:131]
	v_lshl_add_u64 v[134:135], v[170:171], 0, v[132:133]
	global_load_dwordx4 v[200:203], v[130:131], off sc0 nt
	global_load_dwordx4 v[138:141], v[130:131], off offset:256 sc0 nt
	s_nop 0
	global_load_dwordx4 v[130:133], v[134:135], off sc0 nt
	s_nop 0
	global_load_dwordx4 v[134:137], v[134:135], off offset:256 sc0 nt
	s_cmp_lg_u32 s66, 0
	s_waitcnt vmcnt(0)
	v_lshlrev_b32_e32 v172, 16, v142
	v_and_b32_e32 v173, 0xffff0000, v142
	v_lshlrev_b32_e32 v142, 16, v143
	v_and_b32_e32 v143, 0xffff0000, v143
	v_pk_mul_f32 v[128:129], v[128:129], v[142:143]
	v_lshlrev_b32_e32 v204, 16, v144
	v_and_b32_e32 v205, 0xffff0000, v144
	v_lshlrev_b32_e32 v144, 16, v145
	v_lshlrev_b32_e32 v142, 16, v192
	v_and_b32_e32 v143, 0xffff0000, v192
	v_pk_mul_f32 v[110:111], v[110:111], v[142:143]
	v_lshlrev_b32_e32 v142, 16, v193
	v_and_b32_e32 v143, 0xffff0000, v193
	v_pk_mul_f32 v[112:113], v[112:113], v[142:143]
	v_add_u32_e32 v142, 0x90, v160
	v_and_b32_e32 v145, 0xffff0000, v145
	v_ashrrev_i32_e32 v143, 31, v142
	v_pk_mul_f32 v[124:125], v[124:125], v[144:145]
	v_lshlrev_b64 v[144:145], 12, v[142:143]
	v_lshlrev_b32_e32 v206, 16, v178
	v_and_b32_e32 v207, 0xffff0000, v178
	v_lshlrev_b32_e32 v178, 16, v179
	v_and_b32_e32 v179, 0xffff0000, v179
	v_lshlrev_b32_e32 v208, 16, v180
	v_and_b32_e32 v209, 0xffff0000, v180
	v_lshlrev_b32_e32 v180, 16, v181
	v_and_b32_e32 v181, 0xffff0000, v181
	v_lshl_add_u64 v[144:145], v[170:171], 0, v[144:145]
	v_pk_mul_f32 v[96:97], v[96:97], v[178:179]
	v_pk_mul_f32 v[92:93], v[92:93], v[180:181]
	global_load_dwordx4 v[178:181], v[144:145], off sc0 nt
	v_lshlrev_b32_e32 v210, 16, v182
	v_and_b32_e32 v211, 0xffff0000, v182
	v_lshlrev_b32_e32 v182, 16, v183
	v_and_b32_e32 v183, 0xffff0000, v183
	v_lshlrev_b32_e32 v212, 16, v184
	v_and_b32_e32 v213, 0xffff0000, v184
	v_lshlrev_b32_e32 v184, 16, v185
	v_and_b32_e32 v185, 0xffff0000, v185
	v_pk_mul_f32 v[126:127], v[126:127], v[172:173]
	v_pk_mul_f32 v[120:121], v[120:121], v[182:183]
	v_pk_mul_f32 v[116:117], v[116:117], v[184:185]
	v_lshlrev_b32_e32 v172, 16, v194
	v_and_b32_e32 v173, 0xffff0000, v194
	global_load_dwordx4 v[182:185], v[144:145], off offset:256 sc0 nt
	v_lshlrev_b32_e32 v144, 16, v198
	v_and_b32_e32 v145, 0xffff0000, v198
	v_pk_mul_f32 v[106:107], v[106:107], v[172:173]
	v_lshlrev_b32_e32 v172, 16, v195
	v_and_b32_e32 v173, 0xffff0000, v195
	v_pk_mul_f32 v[74:75], v[74:75], v[144:145]
	v_lshlrev_b32_e32 v144, 16, v199
	v_and_b32_e32 v145, 0xffff0000, v199
	v_pk_mul_f32 v[108:109], v[108:109], v[172:173]
	v_lshlrev_b32_e32 v172, 16, v196
	v_and_b32_e32 v173, 0xffff0000, v196
	v_pk_mul_f32 v[76:77], v[76:77], v[144:145]
	v_add_u32_e32 v144, 0xa0, v160
	v_pk_mul_f32 v[78:79], v[78:79], v[172:173]
	v_lshlrev_b32_e32 v172, 16, v197
	v_and_b32_e32 v173, 0xffff0000, v197
	v_ashrrev_i32_e32 v145, 31, v144
	v_pk_mul_f32 v[80:81], v[80:81], v[172:173]
	v_lshlrev_b64 v[172:173], 12, v[144:145]
	v_lshlrev_b32_e32 v214, 16, v186
	v_and_b32_e32 v215, 0xffff0000, v186
	v_lshlrev_b32_e32 v186, 16, v187
	v_and_b32_e32 v187, 0xffff0000, v187
	v_lshlrev_b32_e32 v216, 16, v188
	v_and_b32_e32 v217, 0xffff0000, v188
	v_lshlrev_b32_e32 v188, 16, v189
	v_and_b32_e32 v189, 0xffff0000, v189
	v_lshl_add_u64 v[172:173], v[170:171], 0, v[172:173]
	v_pk_mul_f32 v[88:89], v[88:89], v[186:187]
	v_pk_mul_f32 v[84:85], v[84:85], v[188:189]
	global_load_dwordx4 v[186:189], v[172:173], off sc0 nt
	v_lshlrev_b32_e32 v192, 16, v200
	v_and_b32_e32 v193, 0xffff0000, v200
	v_pk_mul_f32 v[102:103], v[102:103], v[192:193]
	v_lshlrev_b32_e32 v192, 16, v201
	v_and_b32_e32 v193, 0xffff0000, v201
	v_pk_mul_f32 v[104:105], v[104:105], v[192:193]
	v_lshlrev_b32_e32 v192, 16, v202
	v_and_b32_e32 v193, 0xffff0000, v202
	v_pk_mul_f32 v[98:99], v[98:99], v[192:193]
	global_load_dwordx4 v[192:195], v[172:173], off offset:256 sc0 nt
	v_lshlrev_b32_e32 v172, 16, v138
	v_and_b32_e32 v173, 0xffff0000, v138
	v_pk_mul_f32 v[70:71], v[70:71], v[172:173]
	v_add_u32_e32 v172, 0xb0, v160
	v_lshlrev_b32_e32 v138, 16, v139
	v_and_b32_e32 v139, 0xffff0000, v139
	v_ashrrev_i32_e32 v173, 31, v172
	v_pk_mul_f32 v[72:73], v[72:73], v[138:139]
	v_lshlrev_b64 v[138:139], 12, v[172:173]
	v_lshlrev_b32_e32 v196, 16, v203
	v_and_b32_e32 v197, 0xffff0000, v203
	v_lshl_add_u64 v[138:139], v[170:171], 0, v[138:139]
	v_pk_mul_f32 v[100:101], v[100:101], v[196:197]
	global_load_dwordx4 v[196:199], v[138:139], off sc0 nt
	v_lshlrev_b32_e32 v170, 16, v140
	v_and_b32_e32 v171, 0xffff0000, v140
	v_lshlrev_b32_e32 v140, 16, v141
	v_and_b32_e32 v141, 0xffff0000, v141
	v_pk_mul_f32 v[68:69], v[68:69], v[140:141]
	v_lshlrev_b32_e32 v140, 16, v130
	v_and_b32_e32 v141, 0xffff0000, v130
	v_pk_mul_f32 v[62:63], v[62:63], v[140:141]
	global_load_dwordx4 v[138:141], v[138:139], off offset:256 sc0 nt
	v_lshlrev_b32_e32 v130, 16, v131
	v_and_b32_e32 v131, 0xffff0000, v131
	v_pk_mul_f32 v[64:65], v[64:65], v[130:131]
	v_lshlrev_b32_e32 v130, 16, v132
	v_and_b32_e32 v131, 0xffff0000, v132
	v_pk_mul_f32 v[58:59], v[58:59], v[130:131]
	v_lshlrev_b32_e32 v130, 16, v133
	v_and_b32_e32 v131, 0xffff0000, v133
	v_pk_mul_f32 v[60:61], v[60:61], v[130:131]
	v_lshlrev_b32_e32 v130, 16, v134
	v_and_b32_e32 v131, 0xffff0000, v134
	v_pk_mul_f32 v[30:31], v[30:31], v[130:131]
	v_lshlrev_b32_e32 v130, 16, v135
	v_and_b32_e32 v131, 0xffff0000, v135
	v_pk_mul_f32 v[32:33], v[32:33], v[130:131]
	v_lshlrev_b32_e32 v130, 16, v136
	v_and_b32_e32 v131, 0xffff0000, v136
	v_pk_mul_f32 v[26:27], v[26:27], v[130:131]
	v_lshlrev_b32_e32 v130, 16, v137
	v_and_b32_e32 v131, 0xffff0000, v137
	v_pk_mul_f32 v[28:29], v[28:29], v[130:131]
	s_waitcnt vmcnt(0)
; __device__ __forceinline__ unsigned pk_bf16(float lo, float hi) { const f32x2_t v = {lo, hi}; return __builtin_bit_cast(unsigned, __builtin_convertvector(v, bf16x2_t)); }
; __device__ __forceinline__ float bf_lo(unsigned w) { return __uint_as_float(w << 16); }
; __device__ __forceinline__ float bf_hi(unsigned w) { return __uint_as_float(w & 0xffff0000u); }
;     __device__ __forceinline__ bool operator()(f32x4 (&acc)[2][2][4][2], const Unit& u, int wr, int wc, int fr, int fq) const {
;     ...
;                 for (int bj = 0; bj < 2; ++bj) { const u32x4 s = *(const u32x4*)(S + off + bj * HALF);
;                     f32x4 v0 = acc[ai][bj][m][0], v1 = acc[ai][bj][m][1];
;                     v0[0] *= bf_lo(s.x); v0[1] *= bf_hi(s.x); v0[2] *= bf_lo(s.y); v0[3] *= bf_hi(s.y);
;                     v1[0] *= bf_lo(s.z); v1[1] *= bf_hi(s.z); v1[2] *= bf_lo(s.w); v1[3] *= bf_hi(s.w);
;                     acc[ai][bj][m][0] = v0; acc[ai][bj][m][1] = v1; } }
;         if (u.kh == 0) return false;
; #pragma unroll
;         for (int ai = 0; ai < 2; ++ai)
; #pragma unroll
;             for (int m = 0; m < 4; ++m) { const size_t off = (size_t)(r0 + ai * HALF + m * 16) * LDP + c0;
; #pragma unroll
;                 for (int bj = 0; bj < 2; ++bj) { const f32x4 v0 = acc[ai][bj][m][0], v1 = acc[ai][bj][m][1];
;                     u32x4 w; w.x = pk_bf16(v0[0], v0[1]); w.y = pk_bf16(v0[2], v0[3]); w.z = pk_bf16(v1[0], v1[1]); w.w = pk_bf16(v1[2], v1[3]);
;                     *(u32x4*)(MG + off + bj * HALF) = w; } }
	v_lshlrev_b32_e32 v130, 16, v178
	v_and_b32_e32 v131, 0xffff0000, v178
	v_pk_mul_f32 v[54:55], v[54:55], v[130:131]
	v_lshlrev_b32_e32 v130, 16, v179
	v_and_b32_e32 v131, 0xffff0000, v179
	v_pk_mul_f32 v[56:57], v[56:57], v[130:131]
	v_lshlrev_b32_e32 v130, 16, v180
	v_and_b32_e32 v131, 0xffff0000, v180
	v_pk_mul_f32 v[50:51], v[50:51], v[130:131]
	v_lshlrev_b32_e32 v130, 16, v181
	v_and_b32_e32 v131, 0xffff0000, v181
	v_pk_mul_f32 v[52:53], v[52:53], v[130:131]
	v_lshlrev_b32_e32 v130, 16, v182
	v_and_b32_e32 v131, 0xffff0000, v182
	v_pk_mul_f32 v[22:23], v[22:23], v[130:131]
	v_lshlrev_b32_e32 v130, 16, v183
	v_and_b32_e32 v131, 0xffff0000, v183
	v_pk_mul_f32 v[24:25], v[24:25], v[130:131]
	v_lshlrev_b32_e32 v130, 16, v184
	v_and_b32_e32 v131, 0xffff0000, v184
	v_pk_mul_f32 v[18:19], v[18:19], v[130:131]
	v_lshlrev_b32_e32 v130, 16, v185
	v_and_b32_e32 v131, 0xffff0000, v185
	v_pk_mul_f32 v[20:21], v[20:21], v[130:131]
	v_pk_mul_f32 v[122:123], v[122:123], v[204:205]
	v_lshlrev_b32_e32 v130, 16, v186
	v_and_b32_e32 v131, 0xffff0000, v186
	v_pk_mul_f32 v[46:47], v[46:47], v[130:131]
	v_lshlrev_b32_e32 v130, 16, v187
	v_and_b32_e32 v131, 0xffff0000, v187
	v_pk_mul_f32 v[48:49], v[48:49], v[130:131]
	v_lshlrev_b32_e32 v130, 16, v188
	v_and_b32_e32 v131, 0xffff0000, v188
	v_pk_mul_f32 v[42:43], v[42:43], v[130:131]
	v_lshlrev_b32_e32 v130, 16, v189
	v_and_b32_e32 v131, 0xffff0000, v189
	v_pk_mul_f32 v[44:45], v[44:45], v[130:131]
	v_lshlrev_b32_e32 v130, 16, v192
	v_and_b32_e32 v131, 0xffff0000, v192
	v_pk_mul_f32 v[14:15], v[14:15], v[130:131]
	v_lshlrev_b32_e32 v130, 16, v193
	v_and_b32_e32 v131, 0xffff0000, v193
	v_pk_mul_f32 v[16:17], v[16:17], v[130:131]
	v_lshlrev_b32_e32 v130, 16, v194
	v_and_b32_e32 v131, 0xffff0000, v194
	v_pk_mul_f32 v[10:11], v[10:11], v[130:131]
	v_lshlrev_b32_e32 v130, 16, v195
	v_and_b32_e32 v131, 0xffff0000, v195
	v_pk_mul_f32 v[12:13], v[12:13], v[130:131]
	v_lshlrev_b32_e32 v130, 16, v196
	v_and_b32_e32 v131, 0xffff0000, v196
	v_pk_mul_f32 v[38:39], v[38:39], v[130:131]
	v_lshlrev_b32_e32 v130, 16, v197
	v_and_b32_e32 v131, 0xffff0000, v197
	v_pk_mul_f32 v[40:41], v[40:41], v[130:131]
	v_lshlrev_b32_e32 v130, 16, v198
	v_and_b32_e32 v131, 0xffff0000, v198
	v_pk_mul_f32 v[34:35], v[34:35], v[130:131]
	v_lshlrev_b32_e32 v130, 16, v199
	v_and_b32_e32 v131, 0xffff0000, v199
	v_pk_mul_f32 v[36:37], v[36:37], v[130:131]
	v_lshlrev_b32_e32 v130, 16, v138
	v_and_b32_e32 v131, 0xffff0000, v138
	v_pk_mul_f32 v[6:7], v[6:7], v[130:131]
	v_lshlrev_b32_e32 v130, 16, v140
	v_and_b32_e32 v131, 0xffff0000, v140
	v_pk_mul_f32 v[94:95], v[94:95], v[206:207]
	v_pk_mul_f32 v[90:91], v[90:91], v[208:209]
	v_pk_mul_f32 v[118:119], v[118:119], v[210:211]
	v_pk_mul_f32 v[114:115], v[114:115], v[212:213]
	v_pk_mul_f32 v[86:87], v[86:87], v[214:215]
	v_pk_mul_f32 v[82:83], v[82:83], v[216:217]
	v_pk_mul_f32 v[66:67], v[66:67], v[170:171]
	v_pk_mul_f32 v[2:3], v[2:3], v[130:131]
	s_cbranch_scc0 .LBB0_904
	v_mov_b64_e32 v[136:137], s[12:13]
	v_mad_i64_i32 v[134:135], s[0:1], v160, s59, v[136:137]
	v_lshlrev_b64 v[158:159], 1, v[158:159]
	v_cvt_pk_bf16_f32 v130, v126, v127
	v_cvt_pk_bf16_f32 v131, v128, v129
	v_cvt_pk_bf16_f32 v132, v122, v123
	v_cvt_pk_bf16_f32 v133, v124, v125
	v_lshl_add_u64 v[134:135], v[134:135], 0, v[158:159]
	global_store_dwordx4 v[134:135], v[130:133], off
	s_mov_b64 s[40:41], -1
	s_nop 0
	v_cvt_pk_bf16_f32 v130, v94, v95
	v_cvt_pk_bf16_f32 v131, v96, v97
	v_cvt_pk_bf16_f32 v132, v90, v91
	v_cvt_pk_bf16_f32 v133, v92, v93
	global_store_dwordx4 v[134:135], v[130:133], off offset:256
	v_mad_i64_i32 v[134:135], s[0:1], v162, s59, v[136:137]
	s_nop 0
	v_cvt_pk_bf16_f32 v130, v118, v119
	v_cvt_pk_bf16_f32 v131, v120, v121
	v_cvt_pk_bf16_f32 v132, v114, v115
	v_cvt_pk_bf16_f32 v133, v116, v117
	v_lshl_add_u64 v[134:135], v[134:135], 0, v[158:159]
	global_store_dwordx4 v[134:135], v[130:133], off
	s_nop 1
	v_cvt_pk_bf16_f32 v130, v86, v87
	v_cvt_pk_bf16_f32 v131, v88, v89
	v_cvt_pk_bf16_f32 v132, v82, v83
	v_cvt_pk_bf16_f32 v133, v84, v85
	global_store_dwordx4 v[134:135], v[130:133], off offset:256
	v_mad_i64_i32 v[134:135], s[0:1], v164, s59, v[136:137]
	s_nop 0
	v_cvt_pk_bf16_f32 v130, v110, v111
	v_cvt_pk_bf16_f32 v131, v112, v113
	v_cvt_pk_bf16_f32 v132, v106, v107
	v_cvt_pk_bf16_f32 v133, v108, v109
	v_lshl_add_u64 v[134:135], v[134:135], 0, v[158:159]
	global_store_dwordx4 v[134:135], v[130:133], off
	s_nop 1
	v_cvt_pk_bf16_f32 v130, v78, v79
	v_cvt_pk_bf16_f32 v131, v80, v81
	v_cvt_pk_bf16_f32 v132, v74, v75
	v_cvt_pk_bf16_f32 v133, v76, v77
	global_store_dwordx4 v[134:135], v[130:133], off offset:256
	v_mad_i64_i32 v[134:135], s[0:1], v166, s59, v[136:137]
	s_nop 0
	v_cvt_pk_bf16_f32 v130, v102, v103
	v_cvt_pk_bf16_f32 v131, v104, v105
	v_cvt_pk_bf16_f32 v132, v98, v99
	v_cvt_pk_bf16_f32 v133, v100, v101
	v_lshl_add_u64 v[134:135], v[134:135], 0, v[158:159]
	global_store_dwordx4 v[134:135], v[130:133], off
	s_nop 1
	v_cvt_pk_bf16_f32 v130, v70, v71
	v_cvt_pk_bf16_f32 v131, v72, v73
	v_cvt_pk_bf16_f32 v132, v66, v67
	v_cvt_pk_bf16_f32 v133, v68, v69
	global_store_dwordx4 v[134:135], v[130:133], off offset:256
	v_mad_i64_i32 v[134:135], s[0:1], v168, s59, v[136:137]
	s_nop 0
	v_cvt_pk_bf16_f32 v130, v62, v63
	v_cvt_pk_bf16_f32 v131, v64, v65
	v_cvt_pk_bf16_f32 v132, v58, v59
	v_cvt_pk_bf16_f32 v133, v60, v61
	v_lshl_add_u64 v[134:135], v[134:135], 0, v[158:159]
	global_store_dwordx4 v[134:135], v[130:133], off
	s_nop 1
	v_cvt_pk_bf16_f32 v130, v30, v31
	v_cvt_pk_bf16_f32 v131, v32, v33
	v_cvt_pk_bf16_f32 v132, v26, v27
	v_cvt_pk_bf16_f32 v133, v28, v29
	global_store_dwordx4 v[134:135], v[130:133], off offset:256
	v_mad_i64_i32 v[134:135], s[0:1], v142, s59, v[136:137]
	s_nop 0
	v_cvt_pk_bf16_f32 v130, v54, v55
	v_cvt_pk_bf16_f32 v131, v56, v57
	v_cvt_pk_bf16_f32 v132, v50, v51
	v_cvt_pk_bf16_f32 v133, v52, v53
	v_lshl_add_u64 v[134:135], v[134:135], 0, v[158:159]
	global_store_dwordx4 v[134:135], v[130:133], off
	s_nop 1
	v_cvt_pk_bf16_f32 v130, v22, v23
	v_cvt_pk_bf16_f32 v131, v24, v25
	v_cvt_pk_bf16_f32 v132, v18, v19
	v_cvt_pk_bf16_f32 v133, v20, v21
	global_store_dwordx4 v[134:135], v[130:133], off offset:256
	v_mad_i64_i32 v[134:135], s[0:1], v144, s59, v[136:137]
	s_nop 0
	v_cvt_pk_bf16_f32 v130, v46, v47
	v_cvt_pk_bf16_f32 v131, v48, v49
	v_cvt_pk_bf16_f32 v132, v42, v43
	v_cvt_pk_bf16_f32 v133, v44, v45
	v_lshl_add_u64 v[134:135], v[134:135], 0, v[158:159]
	global_store_dwordx4 v[134:135], v[130:133], off
	s_nop 1
	v_cvt_pk_bf16_f32 v130, v14, v15
	v_cvt_pk_bf16_f32 v131, v16, v17
	v_cvt_pk_bf16_f32 v132, v10, v11
	v_cvt_pk_bf16_f32 v133, v12, v13
	global_store_dwordx4 v[134:135], v[130:133], off offset:256
	v_cvt_pk_bf16_f32 v134, v34, v35
	v_cvt_pk_bf16_f32 v135, v36, v37
	v_mad_i64_i32 v[130:131], s[0:1], v172, s59, v[136:137]
	v_cvt_pk_bf16_f32 v132, v38, v39
	v_cvt_pk_bf16_f32 v133, v40, v41
	v_lshl_add_u64 v[130:131], v[130:131], 0, v[158:159]
	global_store_dwordx4 v[130:131], v[132:135], off
